# plus VALU-free DMA headers (saddr-form LDS DMA) and prologue DMA overlapped with Q processing
# baseline (speedup 1.0000x reference)
; #define LAS __attribute__((address_space(3)))
; __device__ __forceinline__ void q_norm_rope(bf16x8 (&qf)[4], const float* gain, int pos, int hi_) {
;     const int hi = lane_now() >> 5; (void)hi_;
;     float x[4][8]; float ss = 0.f;
; #pragma unroll
;     for (int ks = 0; ks < 4; ++ks) { const u32x4 w = __builtin_bit_cast(u32x4, qf[ks]);
; #pragma unroll
;         for (int i = 0; i < 4; ++i) { x[ks][2 * i] = bf_lo(w[i]); x[ks][2 * i + 1] = bf_hi(w[i]); } }
; #pragma unroll
;     for (int ks = 0; ks < 4; ++ks)
; #pragma unroll
;         for (int j = 0; j < 8; ++j) ss += x[ks][j] * x[ks][j];
;     ss = half_sum(ss);
;     const float rstd = 1.0f / sqrtf(ss * (1.f / 64.f) + EPS);
;     const float fpos = (float)pos;
; #pragma unroll
;     for (int ks = 0; ks < 2; ++ks) {
;         const f32x4 ga = *(const f32x4*)(gain + 16 * ks + 8 * hi), gb = *(const f32x4*)(gain + 16 * ks + 8 * hi + 4);
;         const f32x4 gc = *(const f32x4*)(gain + 32 + 16 * ks + 8 * hi), gd = *(const f32x4*)(gain + 32 + 16 * ks + 8 * hi + 4);
; #pragma unroll
;         for (int j = 0; j < 8; ++j) {
;             const int d = 16 * ks + 8 * hi + j;
;             const float invf = exp2f(-(float)d * (13.287712379549449f / 32.f));
;             const float ang = fpos * invf;
; template <bool FIXM> __device__ __forceinline__ void diff_unit(int b, int h, int qb, float lam, const bf16* U, const bf16* VTa, bf16* Y, const float* subg, const float* qgain, const int* pos, unsigned char* lds, int tid, int wid, int lane) {
;     ...
;         { const bf16* qp = U + (rowbase + tq) * EU + C_QA + (2 * h + c) * 64 + hi * 8; bf16x8 qraw[4];
; #pragma unroll
;           for (int ks = 0; ks < 4; ++ks) qraw[ks] = *(const bf16x8*)(qp + ks * 16);
;           q_norm_rope(qraw, qgain, pos[rowbase + tq], hi);
; #pragma unroll
;           for (int ks = 0; ks < 4; ++ks) *(LAS bf16x8*)(qlds + ks * 1024) = qraw[ks]; }
;     ...
;         const int srow = 8 * wid + (lane >> 3), sch = (lane & 7) ^ ((srow >> 1) & 7);
;         const char* kb_u = (const char*)(U + rowbase * EU + C_KA + (2 * h + c) * 64);
;         const char* vb_u = (const char*)(VTa + (size_t)(h * 128) * M + rowbase);
;         const unsigned koff = (unsigned)(srow * EU + 8 * sch) * 2u, voff = (unsigned)(srow * M + 8 * sch) * 2u;
;         LAS unsigned char* ldsl = (LAS unsigned char*)lds + wid * 1024;
;     ...
;         DMA_GROUP(-3); DMA_GROUP(-2); DMA_GROUP(-1);
.LBB0_382:
	s_or_b32 s84, s0, s90
	s_lshl_b64 s[6:7], s[84:85], 1
	v_lshl_add_u64 v[2:3], v[198:199], 0, s[6:7]
	global_load_dwordx4 v[34:37], v[2:3], off
	global_load_dwordx4 v[42:45], v[2:3], off offset:32
	global_load_dwordx4 v[38:41], v[2:3], off offset:64
	global_load_dwordx4 v[46:49], v[2:3], off offset:96
	global_load_dword v0, v[200:201], off
	v_mbcnt_lo_u32_b32 v2, -1, 0
	v_mbcnt_hi_u32_b32 v2, -1, v2
	v_readlane_b32 s8, v252, 18
	v_ashrrev_i32_e32 v68, 2, v2
	v_and_b32_e32 v66, -8, v68
	v_add_u32_e32 v50, 23, v66
	v_cvt_f32_i32_e32 v50, v50
	v_add_u32_e32 v54, 21, v66
	v_cvt_f32_i32_e32 v54, v54
	v_add_u32_e32 v58, 19, v66
	v_mul_f32_e32 v51, 0xbed49a78, v50
	v_cmp_gt_f32_e32 vcc, s3, v51
	v_mul_f32_e32 v55, 0xbed49a78, v54
	v_cvt_f32_i32_e32 v58, v58
	v_cndmask_b32_e32 v51, 0, v225, vcc
	v_fmac_f32_e32 v51, 0xbed49a78, v50
	v_exp_f32_e32 v50, v51
	v_cndmask_b32_e32 v51, 0, v226, vcc
	v_mul_f32_e32 v59, 0xbed49a78, v58
	v_add_u32_e32 v63, 17, v66
	v_ldexp_f32 v50, v50, v51
	v_cvt_f32_i32_e32 v63, v63
	v_add_u32_e32 v62, 16, v66
	v_cvt_f32_i32_e32 v62, v62
	v_ashrrev_i32_e32 v67, 31, v66
	v_mul_f32_e32 v64, 0xbed49a78, v63
	v_readlane_b32 s22, v252, 32
	v_readlane_b32 s23, v252, 33
	s_mov_b32 s0, 0xf800000
	s_mov_b32 m0, s67
	v_lshl_add_u64 v[30:31], v[66:67], 2, s[22:23]
	v_or_b32_e32 v67, 7, v68
	v_cvt_f32_i32_e32 v67, v67
	global_load_dwordx4 v[2:5], v[30:31], off
	global_load_dwordx4 v[10:13], v[30:31], off offset:16
	global_load_dwordx4 v[6:9], v[30:31], off offset:128
	global_load_dwordx4 v[14:17], v[30:31], off offset:144
	global_load_dwordx4 v[18:21], v[30:31], off offset:64
	global_load_dwordx4 v[26:29], v[30:31], off offset:80
	global_load_dwordx4 v[22:25], v[30:31], off offset:192
	s_nop 0
	global_load_dwordx4 v[30:33], v[30:31], off offset:208
	s_add_u32 s98, s68, s6
	s_addc_u32 s99, s69, s7
	v_lshl_add_u64 v[220:221], s[98:99], 0, v[202:203]
	s_mov_b32 m0, s67
	v_readlane_b32 s98, v251, 23
	v_lshl_add_u64 v[254:255], v[220:221], 0, s[86:87]
	global_load_lds_dwordx4 v[254:255], off
	s_mov_b32 m0, s98
	v_readlane_b32 s98, v251, 24
	global_load_lds_dwordx4 v[206:207], off
	s_mov_b32 m0, s98
	s_mov_b64 s[98:99], 0x58400
	v_lshl_add_u64 v[254:255], v[220:221], 0, s[98:99]
	v_readlane_b32 s98, v251, 29
	global_load_lds_dwordx4 v[208:209], off
	s_mov_b32 m0, s98
	v_readlane_b32 s98, v251, 30
	global_load_lds_dwordx4 v[254:255], off
	s_mov_b32 m0, s98
	v_readlane_b32 s98, v251, 31
	global_load_lds_dwordx4 v[206:207], off
	s_mov_b32 m0, s98
	s_mov_b64 s[98:99], 0xb0400
	global_load_lds_dwordx4 v[208:209], off
	v_lshl_add_u64 v[254:255], v[220:221], 0, s[98:99]
	s_mov_b32 m0, s94
	s_nop 0
	global_load_lds_dwordx4 v[254:255], off
	s_mov_b32 m0, s95
	s_nop 0
	global_load_lds_dwordx4 v[210:211], off
	s_mov_b32 m0, s70
	s_nop 0
	global_load_lds_dwordx4 v[212:213], off
	v_readlane_b32 s9, v252, 19
	v_readlane_b32 s10, v252, 20
	v_mul_f32_e32 v68, 0xbed49a78, v67
	v_readlane_b32 s11, v252, 21
	v_readlane_b32 s12, v252, 22
	v_readlane_b32 s13, v252, 23
	v_readlane_b32 s14, v252, 24
	v_readlane_b32 s15, v252, 25
	v_readlane_b32 s16, v252, 26
	v_readlane_b32 s17, v252, 27
	v_readlane_b32 s18, v252, 28
	v_readlane_b32 s19, v252, 29
	v_readlane_b32 s20, v252, 30
	v_readlane_b32 s21, v252, 31
	s_waitcnt vmcnt(9)
	v_and_b32_e32 v99, 0xffff0000, v34
	v_lshlrev_b32_e32 v98, 16, v34
	s_waitcnt vmcnt(20)
	v_lshlrev_b32_e32 v82, 16, v45
	v_and_b32_e32 v83, 0xffff0000, v45
	s_waitcnt vmcnt(17)
	v_cvt_f32_i32_e32 v0, v0
	v_lshlrev_b32_e32 v84, 16, v49
	v_and_b32_e32 v85, 0xffff0000, v49
	v_lshlrev_b32_e32 v86, 16, v44
	v_mul_f32_e32 v50, v50, v0
	v_mul_f32_e32 v51, 0.15915494, v50
	v_rndne_f32_e32 v51, v51
	v_fmac_f32_e32 v50, 0xc0c90fdb, v51
	v_fmac_f32_e32 v50, 0x343bbd2e, v51
	v_mul_f32_e32 v50, 0.15915494, v50
	v_sin_f32_e32 v51, v50
	v_cos_f32_e32 v53, v50
	v_add_u32_e32 v50, 22, v66
	v_cvt_f32_i32_e32 v50, v50
	v_and_b32_e32 v87, 0xffff0000, v44
	v_lshlrev_b32_e32 v44, 16, v48
	v_and_b32_e32 v45, 0xffff0000, v48
	v_mul_f32_e32 v52, 0xbed49a78, v50
	v_cmp_gt_f32_e32 vcc, s3, v52
	v_lshlrev_b32_e32 v48, 16, v43
	v_and_b32_e32 v49, 0xffff0000, v43
	v_cndmask_b32_e32 v52, 0, v225, vcc
	v_fmac_f32_e32 v52, 0xbed49a78, v50
	v_exp_f32_e32 v50, v52
	v_cndmask_b32_e32 v52, 0, v226, vcc
	v_cmp_gt_f32_e32 vcc, s3, v55
	v_lshlrev_b32_e32 v88, 16, v47
	v_ldexp_f32 v50, v50, v52
	v_cndmask_b32_e32 v55, 0, v225, vcc
	v_fmac_f32_e32 v55, 0xbed49a78, v54
	v_exp_f32_e32 v54, v55
	v_cndmask_b32_e32 v55, 0, v226, vcc
	v_mul_f32_e32 v50, v50, v0
	v_and_b32_e32 v89, 0xffff0000, v47
	v_ldexp_f32 v54, v54, v55
	v_mul_f32_e32 v54, v54, v0
	v_mul_f32_e32 v55, 0.15915494, v54
	v_rndne_f32_e32 v55, v55
	v_fmac_f32_e32 v54, 0xc0c90fdb, v55
	v_fmac_f32_e32 v54, 0x343bbd2e, v55
	v_mul_f32_e32 v54, 0.15915494, v54
	v_sin_f32_e32 v57, v54
	v_cos_f32_e32 v55, v54
	v_add_u32_e32 v54, 20, v66
	v_cvt_f32_i32_e32 v54, v54
	v_lshlrev_b32_e32 v90, 16, v42
	v_and_b32_e32 v91, 0xffff0000, v42
	v_lshlrev_b32_e32 v42, 16, v46
	v_mul_f32_e32 v56, 0xbed49a78, v54
	v_cmp_gt_f32_e32 vcc, s3, v56
	v_and_b32_e32 v43, 0xffff0000, v46
	v_lshlrev_b32_e32 v46, 16, v37
	v_cndmask_b32_e32 v56, 0, v225, vcc
	v_fmac_f32_e32 v56, 0xbed49a78, v54
	v_exp_f32_e32 v54, v56
	v_cndmask_b32_e32 v56, 0, v226, vcc
	v_cmp_gt_f32_e32 vcc, s3, v59
	v_and_b32_e32 v47, 0xffff0000, v37
	v_ldexp_f32 v54, v54, v56
	v_cndmask_b32_e32 v59, 0, v225, vcc
	v_fmac_f32_e32 v59, 0xbed49a78, v58
	v_exp_f32_e32 v58, v59
	v_cndmask_b32_e32 v59, 0, v226, vcc
	v_mul_f32_e32 v54, v54, v0
	v_lshlrev_b32_e32 v92, 16, v41
	v_ldexp_f32 v58, v58, v59
	v_mul_f32_e32 v58, v58, v0
	v_mul_f32_e32 v59, 0.15915494, v58
	v_rndne_f32_e32 v59, v59
; __device__ __forceinline__ void q_norm_rope(bf16x8 (&qf)[4], const float* gain, int pos, int hi_) {
;     ...
;     for (int ks = 0; ks < 2; ++ks) {
;         const f32x4 ga = *(const f32x4*)(gain + 16 * ks + 8 * hi), gb = *(const f32x4*)(gain + 16 * ks + 8 * hi + 4);
;         const f32x4 gc = *(const f32x4*)(gain + 32 + 16 * ks + 8 * hi), gd = *(const f32x4*)(gain + 32 + 16 * ks + 8 * hi + 4);
; #pragma unroll
;         for (int j = 0; j < 8; ++j) {
;             const int d = 16 * ks + 8 * hi + j;
;             const float invf = exp2f(-(float)d * (13.287712379549449f / 32.f));
;             const float ang = fpos * invf;
;             const float kq = rintf(ang * 0.15915494309189535f);
;             float rd = fmaf(-kq, 6.28318548202514648f, ang); rd = fmaf(-kq, -1.74845553e-07f, rd);
;             const float rv = rd * 0.15915494309189535f;
;             const float cs = __builtin_amdgcn_cosf(rv), sn = __builtin_amdgcn_sinf(rv);
	v_fmac_f32_e32 v58, 0xc0c90fdb, v59
	v_fmac_f32_e32 v58, 0x343bbd2e, v59
	v_mul_f32_e32 v58, 0.15915494, v58
	v_sin_f32_e32 v61, v58
	v_cos_f32_e32 v59, v58
	v_add_u32_e32 v58, 18, v66
	v_cvt_f32_i32_e32 v58, v58
	v_and_b32_e32 v93, 0xffff0000, v41
	v_lshlrev_b32_e32 v94, 16, v36
	v_and_b32_e32 v95, 0xffff0000, v36
	v_mul_f32_e32 v60, 0xbed49a78, v58
	v_cmp_gt_f32_e32 vcc, s3, v60
	v_lshlrev_b32_e32 v36, 16, v40
	v_and_b32_e32 v37, 0xffff0000, v40
	v_cndmask_b32_e32 v60, 0, v225, vcc
	v_fmac_f32_e32 v60, 0xbed49a78, v58
	v_exp_f32_e32 v58, v60
	v_cndmask_b32_e32 v60, 0, v226, vcc
	v_cmp_gt_f32_e32 vcc, s3, v64
	v_lshlrev_b32_e32 v40, 16, v35
	v_ldexp_f32 v58, v58, v60
	v_cndmask_b32_e32 v64, 0, v225, vcc
	v_fmac_f32_e32 v64, 0xbed49a78, v63
	v_exp_f32_e32 v63, v64
	v_cndmask_b32_e32 v64, 0, v226, vcc
	v_mul_f32_e32 v58, v58, v0
	v_and_b32_e32 v41, 0xffff0000, v35
	v_ldexp_f32 v63, v63, v64
	v_mul_f32_e32 v63, v63, v0
	v_mul_f32_e32 v64, 0.15915494, v63
	v_rndne_f32_e32 v64, v64
	v_fmac_f32_e32 v63, 0xc0c90fdb, v64
	v_fmac_f32_e32 v63, 0x343bbd2e, v64
	v_mul_f32_e32 v64, 0xbed49a78, v62
	v_cmp_gt_f32_e32 vcc, s3, v64
	v_lshlrev_b32_e32 v96, 16, v39
	v_and_b32_e32 v97, 0xffff0000, v39
	v_cndmask_b32_e32 v64, 0, v225, vcc
	v_fmac_f32_e32 v64, 0xbed49a78, v62
	v_exp_f32_e32 v62, v64
	v_cndmask_b32_e32 v64, 0, v226, vcc
	v_cmp_gt_f32_e32 vcc, s3, v68
	v_lshlrev_b32_e32 v34, 16, v38
	v_ldexp_f32 v62, v62, v64
	v_cndmask_b32_e32 v68, 0, v225, vcc
	v_fmac_f32_e32 v68, 0xbed49a78, v67
	v_exp_f32_e32 v67, v68
	v_cndmask_b32_e32 v68, 0, v226, vcc
	v_mul_f32_e32 v62, v62, v0
	v_and_b32_e32 v35, 0xffff0000, v38
	v_ldexp_f32 v67, v67, v68
	v_mul_f32_e32 v67, v67, v0
	v_mul_f32_e32 v68, 0.15915494, v67
	v_rndne_f32_e32 v68, v68
	v_fmac_f32_e32 v67, 0xc0c90fdb, v68
	v_fmac_f32_e32 v67, 0x343bbd2e, v68
	v_mul_f32_e32 v67, 0.15915494, v67
	v_sin_f32_e32 v71, v67
	v_cos_f32_e32 v69, v67
	v_or_b32_e32 v67, 6, v66
	v_cvt_f32_i32_e32 v67, v67
	v_mul_f32_e32 v56, 0.15915494, v54
	v_rndne_f32_e32 v56, v56
	v_fmac_f32_e32 v54, 0xc0c90fdb, v56
	v_mul_f32_e32 v68, 0xbed49a78, v67
	v_cmp_gt_f32_e32 vcc, s3, v68
	v_fmac_f32_e32 v54, 0x343bbd2e, v56
	v_mul_f32_e32 v54, 0.15915494, v54
	v_cndmask_b32_e32 v68, 0, v225, vcc
	v_fmac_f32_e32 v68, 0xbed49a78, v67
	v_exp_f32_e32 v67, v68
	v_cndmask_b32_e32 v68, 0, v226, vcc
	v_mul_f32_e32 v60, 0.15915494, v58
	v_sin_f32_e32 v56, v54
	v_ldexp_f32 v67, v67, v68
	v_mul_f32_e32 v67, v67, v0
	v_mul_f32_e32 v68, 0.15915494, v67
	v_rndne_f32_e32 v68, v68
	v_fmac_f32_e32 v67, 0xc0c90fdb, v68
	v_fmac_f32_e32 v67, 0x343bbd2e, v68
	v_mul_f32_e32 v67, 0.15915494, v67
	v_sin_f32_e32 v70, v67
	v_cos_f32_e32 v68, v67
	v_or_b32_e32 v67, 5, v66
	v_cvt_f32_i32_e32 v67, v67
	v_cos_f32_e32 v54, v54
	v_rndne_f32_e32 v60, v60
	v_fmac_f32_e32 v58, 0xc0c90fdb, v60
	v_mul_f32_e32 v72, 0xbed49a78, v67
	v_cmp_gt_f32_e32 vcc, s3, v72
	v_fmac_f32_e32 v58, 0x343bbd2e, v60
	v_mul_f32_e32 v58, 0.15915494, v58
	v_cndmask_b32_e32 v72, 0, v225, vcc
	v_fmac_f32_e32 v72, 0xbed49a78, v67
	v_exp_f32_e32 v67, v72
	v_cndmask_b32_e32 v72, 0, v226, vcc
	v_mul_f32_e32 v64, 0.15915494, v62
	v_sin_f32_e32 v60, v58
	v_ldexp_f32 v67, v67, v72
	v_mul_f32_e32 v67, v67, v0
	v_mul_f32_e32 v72, 0.15915494, v67
	v_rndne_f32_e32 v72, v72
	v_fmac_f32_e32 v67, 0xc0c90fdb, v72
	v_fmac_f32_e32 v67, 0x343bbd2e, v72
	v_mul_f32_e32 v67, 0.15915494, v67
	v_sin_f32_e32 v73, v67
	v_cos_f32_e32 v75, v67
	v_or_b32_e32 v67, 4, v66
	v_cvt_f32_i32_e32 v67, v67
	v_cos_f32_e32 v58, v58
	v_rndne_f32_e32 v64, v64
	v_fmac_f32_e32 v62, 0xc0c90fdb, v64
	v_mul_f32_e32 v72, 0xbed49a78, v67
	v_cmp_gt_f32_e32 vcc, s3, v72
	v_fmac_f32_e32 v62, 0x343bbd2e, v64
	v_mul_f32_e32 v63, 0.15915494, v63
	v_cndmask_b32_e32 v72, 0, v225, vcc
	v_fmac_f32_e32 v72, 0xbed49a78, v67
	v_exp_f32_e32 v67, v72
	v_cndmask_b32_e32 v72, 0, v226, vcc
	v_mul_f32_e32 v62, 0.15915494, v62
	v_sin_f32_e32 v65, v63
	v_ldexp_f32 v67, v67, v72
	v_mul_f32_e32 v67, v67, v0
	v_mul_f32_e32 v72, 0.15915494, v67
	v_rndne_f32_e32 v72, v72
	v_fmac_f32_e32 v67, 0xc0c90fdb, v72
	v_fmac_f32_e32 v67, 0x343bbd2e, v72
	v_mul_f32_e32 v67, 0.15915494, v67
	v_sin_f32_e32 v72, v67
	v_cos_f32_e32 v74, v67
	v_or_b32_e32 v67, 3, v66
	v_cvt_f32_i32_e32 v67, v67
	v_cos_f32_e32 v63, v63
	v_sin_f32_e32 v64, v62
	v_cos_f32_e32 v62, v62
	v_mul_f32_e32 v76, 0xbed49a78, v67
	v_cmp_gt_f32_e32 vcc, s3, v76
	v_mul_f32_e32 v52, 0.15915494, v50
	v_rndne_f32_e32 v52, v52
	v_cndmask_b32_e32 v76, 0, v225, vcc
	v_fmac_f32_e32 v76, 0xbed49a78, v67
	v_exp_f32_e32 v67, v76
	v_cndmask_b32_e32 v76, 0, v226, vcc
	v_fmac_f32_e32 v50, 0xc0c90fdb, v52
	v_fmac_f32_e32 v50, 0x343bbd2e, v52
	v_ldexp_f32 v67, v67, v76
	v_mul_f32_e32 v67, v67, v0
	v_mul_f32_e32 v76, 0.15915494, v67
	v_rndne_f32_e32 v76, v76
	v_fmac_f32_e32 v67, 0xc0c90fdb, v76
	v_fmac_f32_e32 v67, 0x343bbd2e, v76
	v_mul_f32_e32 v67, 0.15915494, v67
	v_sin_f32_e32 v77, v67
	v_cos_f32_e32 v79, v67
	v_or_b32_e32 v67, 2, v66
	v_cvt_f32_i32_e32 v67, v67
	v_mul_f32_e32 v52, 0.15915494, v50
	v_sin_f32_e32 v50, v52
	v_cos_f32_e32 v52, v52
	v_mul_f32_e32 v76, 0xbed49a78, v67
	v_cmp_gt_f32_e32 vcc, s3, v76
	s_nop 1
	v_cndmask_b32_e32 v76, 0, v225, vcc
	v_fmac_f32_e32 v76, 0xbed49a78, v67
	v_exp_f32_e32 v67, v76
	v_cndmask_b32_e32 v76, 0, v226, vcc
	v_ldexp_f32 v67, v67, v76
	v_mul_f32_e32 v67, v67, v0
	v_mul_f32_e32 v76, 0.15915494, v67
	v_rndne_f32_e32 v76, v76
	v_fmac_f32_e32 v67, 0xc0c90fdb, v76
	v_fmac_f32_e32 v67, 0x343bbd2e, v76
	v_mul_f32_e32 v67, 0.15915494, v67
	v_sin_f32_e32 v76, v67
	v_cos_f32_e32 v78, v67
	v_or_b32_e32 v67, 1, v66
	v_cvt_f32_i32_e32 v67, v67
	v_cvt_f32_i32_e32 v66, v66
	v_mul_f32_e32 v80, 0xbed49a78, v67
; __device__ __forceinline__ float half_sum(float m) { auto rr = __builtin_amdgcn_permlane32_swap(__float_as_uint(m), __float_as_uint(m), false, false); return __uint_as_float(rr[0]) + __uint_as_float(rr[1]); }
; __device__ __forceinline__ void q_norm_rope(bf16x8 (&qf)[4], const float* gain, int pos, int hi_) {
;     ...
; #pragma unroll
;     for (int ks = 0; ks < 4; ++ks)
; #pragma unroll
;         for (int j = 0; j < 8; ++j) ss += x[ks][j] * x[ks][j];
;     ss = half_sum(ss);
;     const float rstd = 1.0f / sqrtf(ss * (1.f / 64.f) + EPS);
;     const float fpos = (float)pos;
; #pragma unroll
;     for (int ks = 0; ks < 2; ++ks) {
;         const f32x4 ga = *(const f32x4*)(gain + 16 * ks + 8 * hi), gb = *(const f32x4*)(gain + 16 * ks + 8 * hi + 4);
;         const f32x4 gc = *(const f32x4*)(gain + 32 + 16 * ks + 8 * hi), gd = *(const f32x4*)(gain + 32 + 16 * ks + 8 * hi + 4);
; #pragma unroll
;         for (int j = 0; j < 8; ++j) {
;             const int d = 16 * ks + 8 * hi + j;
;             const float invf = exp2f(-(float)d * (13.287712379549449f / 32.f));
;             const float ang = fpos * invf;
;             const float kq = rintf(ang * 0.15915494309189535f);
;             float rd = fmaf(-kq, 6.28318548202514648f, ang); rd = fmaf(-kq, -1.74845553e-07f, rd);
;             const float rv = rd * 0.15915494309189535f;
;             const float cs = __builtin_amdgcn_cosf(rv), sn = __builtin_amdgcn_sinf(rv);
	v_cmp_gt_f32_e32 vcc, s3, v80
	s_nop 1
	v_cndmask_b32_e32 v80, 0, v225, vcc
	v_fmac_f32_e32 v80, 0xbed49a78, v67
	v_exp_f32_e32 v67, v80
	v_cndmask_b32_e32 v80, 0, v226, vcc
	v_ldexp_f32 v67, v67, v80
	v_mul_f32_e32 v67, v67, v0
	v_mul_f32_e32 v80, 0.15915494, v67
	v_rndne_f32_e32 v80, v80
	v_fmac_f32_e32 v67, 0xc0c90fdb, v80
	v_fmac_f32_e32 v67, 0x343bbd2e, v80
	v_mul_f32_e32 v80, 0.15915494, v67
	v_sin_f32_e32 v67, v80
	v_cos_f32_e32 v81, v80
	v_mul_f32_e32 v80, 0xbed49a78, v66
	v_cmp_gt_f32_e32 vcc, s3, v80
	s_nop 1
	v_cndmask_b32_e32 v80, 0, v225, vcc
	v_fmac_f32_e32 v80, 0xbed49a78, v66
	v_exp_f32_e32 v66, v80
	v_cndmask_b32_e32 v80, 0, v226, vcc
	v_ldexp_f32 v66, v66, v80
	v_mul_f32_e32 v0, v66, v0
	v_mul_f32_e32 v66, 0.15915494, v0
	v_rndne_f32_e32 v66, v66
	v_fmac_f32_e32 v0, 0xc0c90fdb, v66
	v_fmac_f32_e32 v0, 0x343bbd2e, v66
	v_mul_f32_e32 v0, 0.15915494, v0
	v_sin_f32_e32 v66, v0
	v_cos_f32_e32 v80, v0
	v_mul_f32_e32 v0, v99, v99
	v_pk_fma_f32 v[38:39], v[98:99], v[98:99], v[0:1] op_sel_hi:[1,1,0]
	v_mul_f32_e32 v0, v41, v41
	v_pk_fma_f32 v[38:39], v[40:41], v[40:41], v[38:39]
	s_nop 0
	v_pk_add_f32 v[38:39], v[0:1], v[38:39] op_sel_hi:[0,1]
	v_pk_fma_f32 v[38:39], v[94:95], v[94:95], v[38:39]
	v_mul_f32_e32 v0, v95, v95
	v_pk_add_f32 v[38:39], v[0:1], v[38:39] op_sel_hi:[0,1]
	v_pk_fma_f32 v[38:39], v[46:47], v[46:47], v[38:39]
	v_mul_f32_e32 v0, v47, v47
	v_pk_add_f32 v[38:39], v[0:1], v[38:39] op_sel_hi:[0,1]
	v_pk_fma_f32 v[38:39], v[90:91], v[90:91], v[38:39]
	v_mul_f32_e32 v0, v91, v91
	v_pk_add_f32 v[38:39], v[0:1], v[38:39] op_sel_hi:[0,1]
	v_pk_fma_f32 v[38:39], v[48:49], v[48:49], v[38:39]
	v_mul_f32_e32 v0, v49, v49
	v_pk_add_f32 v[38:39], v[0:1], v[38:39] op_sel_hi:[0,1]
	v_pk_fma_f32 v[38:39], v[86:87], v[86:87], v[38:39]
	v_mul_f32_e32 v0, v87, v87
	v_pk_add_f32 v[38:39], v[0:1], v[38:39] op_sel_hi:[0,1]
	v_pk_fma_f32 v[38:39], v[82:83], v[82:83], v[38:39]
	v_mul_f32_e32 v0, v83, v83
	v_pk_add_f32 v[38:39], v[0:1], v[38:39] op_sel_hi:[0,1]
	v_pk_fma_f32 v[38:39], v[34:35], v[34:35], v[38:39]
	v_mul_f32_e32 v0, v35, v35
	v_pk_add_f32 v[38:39], v[0:1], v[38:39] op_sel_hi:[0,1]
	v_pk_fma_f32 v[38:39], v[96:97], v[96:97], v[38:39]
	v_mul_f32_e32 v0, v97, v97
	v_pk_add_f32 v[38:39], v[0:1], v[38:39] op_sel_hi:[0,1]
	v_pk_fma_f32 v[38:39], v[36:37], v[36:37], v[38:39]
	v_mul_f32_e32 v0, v37, v37
	v_pk_add_f32 v[38:39], v[0:1], v[38:39] op_sel_hi:[0,1]
	v_pk_fma_f32 v[38:39], v[92:93], v[92:93], v[38:39]
	v_mul_f32_e32 v0, v93, v93
	v_pk_add_f32 v[38:39], v[0:1], v[38:39] op_sel_hi:[0,1]
	v_pk_fma_f32 v[38:39], v[42:43], v[42:43], v[38:39]
	v_mul_f32_e32 v0, v43, v43
	v_pk_add_f32 v[38:39], v[0:1], v[38:39] op_sel_hi:[0,1]
	v_pk_fma_f32 v[38:39], v[88:89], v[88:89], v[38:39]
	v_mul_f32_e32 v0, v89, v89
	v_pk_add_f32 v[38:39], v[0:1], v[38:39] op_sel_hi:[0,1]
	v_pk_fma_f32 v[38:39], v[44:45], v[44:45], v[38:39]
	v_mul_f32_e32 v0, v45, v45
	v_pk_add_f32 v[38:39], v[0:1], v[38:39] op_sel_hi:[0,1]
	v_pk_fma_f32 v[38:39], v[84:85], v[84:85], v[38:39]
	v_mul_f32_e32 v0, v85, v85
	v_pk_add_f32 v[38:39], v[0:1], v[38:39] op_sel_hi:[0,1]
	v_mov_b32_e32 v0, v38
	s_nop 1
	v_permlane32_swap_b32_e32 v38, v0
	v_add_f32_e32 v0, v38, v0
	v_fmamk_f32 v0, v0, 0x3c800000, v223
	v_cmp_gt_f32_e32 vcc, s0, v0
	v_mul_f32_e32 v38, 0x4f800000, v0
	s_nop 0
	v_cndmask_b32_e32 v0, v0, v38, vcc
	v_sqrt_f32_e32 v38, v0
	s_nop 0
	v_add_u32_e32 v39, -1, v38
	v_fma_f32 v100, -v39, v38, v0
	v_cmp_ge_f32_e64 s[0:1], 0, v100
	v_add_u32_e32 v100, 1, v38
	s_nop 0
	v_cndmask_b32_e64 v39, v38, v39, s[0:1]
	v_fma_f32 v38, -v100, v38, v0
	v_cmp_lt_f32_e64 s[0:1], 0, v38
	s_nop 1
	v_cndmask_b32_e64 v38, v39, v100, s[0:1]
	v_mul_f32_e32 v39, 0x37800000, v38
	v_cndmask_b32_e32 v38, v38, v39, vcc
	v_cmp_class_f32_e32 vcc, v0, v224
	s_nop 1
	v_cndmask_b32_e32 v0, v38, v0, vcc
	v_div_scale_f32 v38, s[0:1], v0, v0, 1.0
	v_rcp_f32_e32 v39, v38
	s_add_u32 s0, s68, s6
	s_addc_u32 s1, s69, s7
	s_add_u32 s100, s0, 0x400
	s_addc_u32 s101, s1, 0
	v_lshl_add_u64 v[220:221], s[0:1], 0, v[202:203]
	v_fma_f32 v100, -v38, v39, 1.0
	v_fmac_f32_e32 v39, v100, v39
	v_div_scale_f32 v100, vcc, 1.0, v0, 1.0
	v_mul_f32_e32 v101, v100, v39
	v_fma_f32 v102, -v38, v101, v100
	v_fmac_f32_e32 v101, v102, v39
	v_fma_f32 v38, -v38, v101, v100
	v_div_fmas_f32 v38, v38, v39, v101
	v_div_fixup_f32 v0, v38, v0, 1.0
	v_pk_mul_f32 v[38:39], v[0:1], v[82:83] op_sel_hi:[0,1]
	s_waitcnt vmcnt(11)
	v_pk_mul_f32 v[28:29], v[28:29], v[38:39]
	v_pk_mul_f32 v[38:39], v[0:1], v[84:85] op_sel_hi:[0,1]
	s_waitcnt vmcnt(9)
; #define LAS __attribute__((address_space(3)))
; __device__ __forceinline__ unsigned cvtpk(float lo, float hi) { f32x2_t v = {lo, hi}; bf16x2_t b = __builtin_convertvector(v, bf16x2_t); return __builtin_bit_cast(unsigned, b); }
; #define DMA_GROUP(t_) do { const int kt_ = ((t_) + 3 < NT) ? (t_) + 3 : NT - 1; int vt_ = ((t_) + 2 < NT) ? (t_) + 2 : NT - 1; vt_ = vt_ < 0 ? 0 : vt_; DMA_K(kt_, ((t_) + 3) & 3); DMA_V(vt_, ((t_) + 2) & 3); } while (0)
; __device__ __forceinline__ void q_norm_rope(bf16x8 (&qf)[4], const float* gain, int pos, int hi_) {
;     ...
;             const float g1 = (j < 4) ? ga[j & 3] : gb[j & 3], g2 = (j < 4) ? gc[j & 3] : gd[j & 3];
;             const float y1 = x[ks][j] * rstd * g1, y2 = x[ks + 2][j] * rstd * g2;
;             x[ks][j] = (y1 * cs - y2 * sn) * QS; x[ks + 2][j] = (y2 * cs + y1 * sn) * QS;
;         }
;     }
; #pragma unroll
;     for (int ks = 0; ks < 4; ++ks) { u32x4 w;
; #pragma unroll
;         for (int i = 0; i < 4; ++i) w[i] = cvtpk(x[ks][2 * i], x[ks][2 * i + 1]);
;         qf[ks] = __builtin_bit_cast(bf16x8, w); }
; template <bool FIXM> __device__ __forceinline__ void diff_unit(int b, int h, int qb, float lam, const bf16* U, const bf16* VTa, bf16* Y, const float* subg, const float* qgain, const int* pos, unsigned char* lds, int tid, int wid, int lane) {
;     ...
;           for (int ks = 0; ks < 4; ++ks) *(LAS bf16x8*)(qlds + ks * 1024) = qraw[ks]; }
;     ...
;         const int srow = 8 * wid + (lane >> 3), sch = (lane & 7) ^ ((srow >> 1) & 7);
;         const char* kb_u = (const char*)(U + rowbase * EU + C_KA + (2 * h + c) * 64);
;         const char* vb_u = (const char*)(VTa + (size_t)(h * 128) * M + rowbase);
;         const unsigned koff = (unsigned)(srow * EU + 8 * sch) * 2u, voff = (unsigned)(srow * M + 8 * sch) * 2u;
;         LAS unsigned char* ldsl = (LAS unsigned char*)lds + wid * 1024;
;     ...
;         DMA_GROUP(-3); DMA_GROUP(-2); DMA_GROUP(-1);
;         asm volatile("s_waitcnt vmcnt(6)" ::: "memory");
;         __builtin_amdgcn_s_barrier();
	v_pk_mul_f32 v[32:33], v[38:39], v[32:33]
	v_pk_mul_f32 v[38:39], v[0:1], v[86:87] op_sel_hi:[0,1]
	v_pk_mul_f32 v[26:27], v[26:27], v[38:39]
	v_pk_mul_f32 v[38:39], v[0:1], v[44:45] op_sel_hi:[0,1]
	v_pk_mul_f32 v[30:31], v[38:39], v[30:31]
	v_readlane_b32 s0, v251, 23
	v_pk_mul_f32 v[38:39], v[30:31], v[54:55]
	v_pk_mul_f32 v[30:31], v[30:31], v[56:57]
	v_pk_fma_f32 v[38:39], v[26:27], v[56:57], v[38:39]
	v_pk_fma_f32 v[26:27], v[26:27], v[54:55], v[30:31] neg_lo:[0,0,1] neg_hi:[0,0,1]
	v_pk_mul_f32 v[30:31], v[0:1], v[48:49] op_sel_hi:[0,1]
	v_pk_mul_f32 v[20:21], v[20:21], v[30:31]
	v_pk_mul_f32 v[30:31], v[0:1], v[88:89] op_sel_hi:[0,1]
	v_pk_mul_f32 v[24:25], v[24:25], v[30:31]
	v_pk_mul_f32 v[38:39], v[38:39], s[66:67] op_sel_hi:[1,0]
	v_pk_mul_f32 v[30:31], v[24:25], v[58:59]
	v_pk_mul_f32 v[24:25], v[24:25], v[60:61]
	v_pk_fma_f32 v[30:31], v[20:21], v[60:61], v[30:31]
	v_pk_fma_f32 v[20:21], v[20:21], v[58:59], v[24:25] neg_lo:[0,0,1] neg_hi:[0,0,1]
	v_pk_mul_f32 v[24:25], v[0:1], v[90:91] op_sel_hi:[0,1]
	v_pk_mul_f32 v[18:19], v[18:19], v[24:25]
	v_pk_mul_f32 v[24:25], v[0:1], v[42:43] op_sel_hi:[0,1]
	v_pk_mul_f32 v[22:23], v[22:23], v[24:25]
	v_pk_mul_f32 v[26:27], v[26:27], s[66:67] op_sel_hi:[1,0]
	v_pk_mul_f32 v[24:25], v[22:23], v[62:63]
	v_pk_mul_f32 v[22:23], v[22:23], v[64:65]
	v_pk_fma_f32 v[24:25], v[18:19], v[64:65], v[24:25]
	v_pk_fma_f32 v[18:19], v[18:19], v[62:63], v[22:23] neg_lo:[0,0,1] neg_hi:[0,0,1]
	v_pk_mul_f32 v[22:23], v[0:1], v[46:47] op_sel_hi:[0,1]
	v_pk_mul_f32 v[12:13], v[12:13], v[22:23]
	v_pk_mul_f32 v[22:23], v[0:1], v[92:93] op_sel_hi:[0,1]
	v_pk_mul_f32 v[16:17], v[16:17], v[22:23]
	v_pk_mul_f32 v[30:31], v[30:31], s[66:67] op_sel_hi:[1,0]
	v_pk_mul_f32 v[22:23], v[16:17], v[68:69]
	v_pk_mul_f32 v[16:17], v[16:17], v[70:71]
	v_pk_fma_f32 v[22:23], v[12:13], v[70:71], v[22:23]
	v_pk_fma_f32 v[12:13], v[12:13], v[68:69], v[16:17] neg_lo:[0,0,1] neg_hi:[0,0,1]
	v_pk_mul_f32 v[16:17], v[0:1], v[94:95] op_sel_hi:[0,1]
	v_pk_mul_f32 v[10:11], v[10:11], v[16:17]
	v_pk_mul_f32 v[16:17], v[0:1], v[36:37] op_sel_hi:[0,1]
	v_pk_mul_f32 v[14:15], v[14:15], v[16:17]
	v_pk_mul_f32 v[12:13], v[12:13], s[66:67] op_sel_hi:[1,0]
	v_pk_mul_f32 v[16:17], v[14:15], v[74:75]
	v_pk_mul_f32 v[14:15], v[14:15], v[72:73]
	v_pk_fma_f32 v[16:17], v[10:11], v[72:73], v[16:17]
	v_pk_fma_f32 v[10:11], v[10:11], v[74:75], v[14:15] neg_lo:[0,0,1] neg_hi:[0,0,1]
	v_pk_mul_f32 v[14:15], v[0:1], v[40:41] op_sel_hi:[0,1]
	v_pk_mul_f32 v[4:5], v[4:5], v[14:15]
	v_pk_mul_f32 v[14:15], v[0:1], v[96:97] op_sel_hi:[0,1]
	v_pk_mul_f32 v[8:9], v[8:9], v[14:15]
	v_pk_mul_f32 v[10:11], v[10:11], s[66:67] op_sel_hi:[1,0]
	v_pk_mul_f32 v[14:15], v[8:9], v[78:79]
	v_pk_mul_f32 v[8:9], v[8:9], v[76:77]
	v_pk_fma_f32 v[14:15], v[4:5], v[76:77], v[14:15]
	v_pk_fma_f32 v[4:5], v[4:5], v[78:79], v[8:9] neg_lo:[0,0,1] neg_hi:[0,0,1]
	v_pk_mul_f32 v[8:9], v[0:1], v[98:99] op_sel_hi:[0,1]
	v_pk_mul_f32 v[2:3], v[2:3], v[8:9]
	v_pk_mul_f32 v[8:9], v[0:1], v[34:35] op_sel_hi:[0,1]
	v_pk_mul_f32 v[6:7], v[6:7], v[8:9]
	v_pk_mul_f32 v[4:5], v[4:5], s[66:67] op_sel_hi:[1,0]
	v_pk_mul_f32 v[8:9], v[6:7], v[80:81]
	v_pk_mul_f32 v[6:7], v[6:7], v[66:67]
	v_pk_fma_f32 v[8:9], v[2:3], v[66:67], v[8:9]
	v_pk_fma_f32 v[2:3], v[2:3], v[80:81], v[6:7] neg_lo:[0,0,1] neg_hi:[0,0,1]
	v_pk_mul_f32 v[6:7], v[32:33], v[50:51]
	v_pk_mul_f32 v[2:3], v[2:3], s[66:67] op_sel_hi:[1,0]
	v_pk_fma_f32 v[6:7], v[28:29], v[52:53], v[6:7] neg_lo:[0,0,1] neg_hi:[0,0,1]
	v_pk_mul_f32 v[20:21], v[20:21], s[66:67] op_sel_hi:[1,0]
	v_pk_mul_f32 v[36:37], v[6:7], s[66:67] op_sel_hi:[1,0]
	v_pk_mul_f32 v[6:7], v[32:33], v[52:53]
	v_pk_mul_f32 v[24:25], v[24:25], s[66:67] op_sel_hi:[1,0]
	v_pk_fma_f32 v[6:7], v[28:29], v[50:51], v[6:7]
	v_pk_mul_f32 v[18:19], v[18:19], s[66:67] op_sel_hi:[1,0]
	v_pk_mul_f32 v[22:23], v[22:23], s[66:67] op_sel_hi:[1,0]
	v_pk_mul_f32 v[16:17], v[16:17], s[66:67] op_sel_hi:[1,0]
	v_pk_mul_f32 v[14:15], v[14:15], s[66:67] op_sel_hi:[1,0]
	v_pk_mul_f32 v[34:35], v[8:9], s[66:67] op_sel_hi:[1,0]
	v_pk_mul_f32 v[28:29], v[6:7], s[66:67] op_sel_hi:[1,0]
	v_cvt_pk_bf16_f32 v2, v2, v3
	v_cvt_pk_bf16_f32 v3, v4, v5
	v_cvt_pk_bf16_f32 v4, v10, v11
	v_cvt_pk_bf16_f32 v5, v12, v13
	v_cvt_pk_bf16_f32 v6, v18, v19
	v_cvt_pk_bf16_f32 v7, v20, v21
	v_cvt_pk_bf16_f32 v8, v26, v27
	v_cvt_pk_bf16_f32 v9, v36, v37
	v_cvt_pk_bf16_f32 v10, v34, v35
	v_cvt_pk_bf16_f32 v11, v14, v15
	v_cvt_pk_bf16_f32 v12, v16, v17
	v_cvt_pk_bf16_f32 v13, v22, v23
	v_cvt_pk_bf16_f32 v14, v24, v25
	v_cvt_pk_bf16_f32 v15, v30, v31
	v_cvt_pk_bf16_f32 v16, v38, v39
	v_cvt_pk_bf16_f32 v17, v28, v29
	ds_write_b128 v241, v[2:5]
	ds_write_b128 v241, v[6:9] offset:1024
	ds_write_b128 v241, v[10:13] offset:2048
	ds_write_b128 v241, v[14:17] offset:3072
	s_mov_b64 s[0:1], 0x108400
	v_lshl_add_u64 v[2:3], v[220:221], 0, s[0:1]
	v_readlane_b32 s0, v251, 25
	s_mov_b32 m0, s71
	s_waitcnt vmcnt(6)
	s_barrier
	global_load_lds_dwordx4 v[2:3], off
	s_mov_b32 m0, s0
	v_readlane_b32 s0, v251, 26
	global_load_lds_dwordx4 v[214:215], off
	s_mov_b32 m0, s0
	v_add_u32_e32 v0, v229, v232
	global_load_lds_dwordx4 v[216:217], off
	ds_read_b128 v[2:5], v0
	ds_read_b128 v[6:9], v241
	ds_read_b128 v[10:13], v0 offset:4096
	ds_read_b128 v[36:39], v241 offset:1024
	s_waitcnt lgkmcnt(0)
	v_mfma_f32_32x32x16_bf16 v[20:35], v[2:5], v[6:9], 0
	v_add_u32_e32 v0, v229, v234
	ds_read_b128 v[40:43], v0
	v_mfma_f32_32x32x16_bf16 v[4:19], v[10:13], v[6:9], 0
	ds_read_b128 v[44:47], v0 offset:4096
	ds_read_b128 v[48:51], v241 offset:2048
	s_waitcnt lgkmcnt(0)
	v_mfma_f32_32x32x16_bf16 v[20:35], v[40:43], v[36:39], v[20:35]
	v_add_u32_e32 v0, v229, v236
	ds_read_b128 v[40:43], v0
	v_mfma_f32_32x32x16_bf16 v[4:19], v[44:47], v[36:39], v[4:19]
	ds_read_b128 v[36:39], v0 offset:4096
	ds_read_b128 v[44:47], v241 offset:3072
	s_waitcnt lgkmcnt(0)
	v_mfma_f32_32x32x16_bf16 v[20:35], v[40:43], v[48:51], v[20:35]
	v_add_u32_e32 v0, v229, v238
	ds_read_b128 v[40:43], v0
	v_mfma_f32_32x32x16_bf16 v[4:19], v[36:39], v[48:51], v[4:19]
	ds_read_b128 v[36:39], v0 offset:4096
	s_waitcnt lgkmcnt(0)
	v_mfma_f32_32x32x16_bf16 v[20:35], v[40:43], v[44:47], v[20:35]
	v_mfma_f32_32x32x16_bf16 v[4:19], v[36:39], v[44:47], v[4:19]
	s_andn2_b64 vcc, exec, s[4:5]
	s_cbranch_vccnz .LBB0_384
	v_mov_b32_e32 v0, v231
	s_nop 0
	v_cmp_gt_i32_e64 s[62:63], 22, v0
	v_cmp_gt_i32_e64 s[64:65], 23, v0
	v_cmp_gt_i32_e64 s[60:61], 21, v0
	s_and_b64 s[62:63], s[64:65], s[62:63]
	v_cmp_gt_i32_e64 s[58:59], 20, v0
	s_and_b64 s[60:61], s[62:63], s[60:61]
	v_cmp_gt_i32_e64 s[56:57], 19, v0
	s_and_b64 s[58:59], s[60:61], s[58:59]
	v_cmp_gt_i32_e64 s[54:55], 18, v0
	s_and_b64 s[56:57], s[58:59], s[56:57]
	v_cmp_gt_i32_e64 s[52:53], 17, v0
	s_and_b64 s[54:55], s[56:57], s[54:55]
	v_cmp_gt_i32_e64 s[50:51], 16, v0
	s_and_b64 s[52:53], s[54:55], s[52:53]
	v_cmp_gt_i32_e64 s[48:49], 7, v0
	s_and_b64 s[50:51], s[52:53], s[50:51]
	v_cmp_gt_i32_e64 s[46:47], 6, v0
	s_and_b64 s[48:49], s[50:51], s[48:49]
	v_cmp_gt_i32_e64 s[44:45], 5, v0
	s_and_b64 s[46:47], s[48:49], s[46:47]
	v_cmp_gt_i32_e64 s[42:43], 4, v0
	s_and_b64 s[44:45], s[46:47], s[44:45]
	v_cmp_gt_i32_e64 s[40:41], 3, v0
	s_and_b64 s[42:43], s[44:45], s[42:43]
	v_cmp_gt_i32_e64 s[38:39], 2, v0
	s_and_b64 s[40:41], s[42:43], s[40:41]
	v_cmp_gt_i32_e64 s[36:37], 1, v0
	s_and_b64 s[38:39], s[40:41], s[38:39]
	v_cmp_gt_i32_e64 s[34:35], 0, v0
	s_and_b64 s[36:37], s[38:39], s[36:37]
	s_and_b64 s[34:35], s[36:37], s[34:35]
	v_cmp_gt_i32_e64 s[30:31], 54, v0
	v_cndmask_b32_e64 v20, v20, v227, s[34:35]
	v_cmp_gt_i32_e64 s[34:35], 55, v0
	v_cmp_gt_i32_e64 s[28:29], 53, v0
	s_and_b64 s[30:31], s[34:35], s[30:31]
	v_cmp_gt_i32_e64 s[26:27], 52, v0
	s_and_b64 s[28:29], s[30:31], s[28:29]
	v_cmp_gt_i32_e64 s[24:25], 51, v0
	s_and_b64 s[26:27], s[28:29], s[26:27]
	v_cmp_gt_i32_e64 s[22:23], 50, v0
	s_and_b64 s[24:25], s[26:27], s[24:25]
	v_cmp_gt_i32_e64 s[20:21], 49, v0
	s_and_b64 s[22:23], s[24:25], s[22:23]
	v_cmp_gt_i32_e64 s[18:19], 48, v0
	s_and_b64 s[20:21], s[22:23], s[20:21]
	v_cmp_gt_i32_e64 s[16:17], 39, v0
	s_and_b64 s[18:19], s[20:21], s[18:19]
	v_cmp_gt_i32_e64 s[14:15], 38, v0
	s_and_b64 s[16:17], s[18:19], s[16:17]
	v_cmp_gt_i32_e64 s[12:13], 37, v0
	s_and_b64 s[14:15], s[16:17], s[14:15]
	v_cmp_gt_i32_e64 s[10:11], 36, v0
	s_and_b64 s[12:13], s[14:15], s[12:13]
	v_cmp_gt_i32_e64 s[8:9], 35, v0
	s_and_b64 s[10:11], s[12:13], s[10:11]
	v_cmp_gt_i32_e64 s[6:7], 34, v0
	s_and_b64 s[8:9], s[10:11], s[8:9]
	v_cmp_gt_i32_e64 s[0:1], 33, v0
	s_and_b64 s[6:7], s[8:9], s[6:7]
	v_cmp_gt_i32_e32 vcc, 32, v0
	s_and_b64 s[0:1], s[6:7], s[0:1]
	s_and_b64 vcc, s[0:1], vcc
	v_cndmask_b32_e64 v35, v35, v227, s[64:65]
	v_cndmask_b32_e64 v34, v34, v227, s[62:63]
	v_cndmask_b32_e64 v33, v33, v227, s[60:61]
	v_cndmask_b32_e64 v32, v32, v227, s[58:59]
	v_cndmask_b32_e64 v31, v31, v227, s[56:57]
	v_cndmask_b32_e64 v30, v30, v227, s[54:55]
	v_cndmask_b32_e64 v29, v29, v227, s[52:53]
	v_cndmask_b32_e64 v28, v28, v227, s[50:51]
	v_cndmask_b32_e64 v27, v27, v227, s[48:49]
	v_cndmask_b32_e64 v26, v26, v227, s[46:47]
	v_cndmask_b32_e64 v25, v25, v227, s[44:45]
	v_cndmask_b32_e64 v24, v24, v227, s[42:43]
	v_cndmask_b32_e64 v23, v23, v227, s[40:41]
	v_cndmask_b32_e64 v22, v22, v227, s[38:39]
	v_cndmask_b32_e64 v21, v21, v227, s[36:37]
	v_cndmask_b32_e64 v19, v19, v227, s[34:35]
	v_cndmask_b32_e64 v18, v18, v227, s[30:31]
	v_cndmask_b32_e64 v17, v17, v227, s[28:29]
	v_cndmask_b32_e64 v16, v16, v227, s[26:27]
	v_cndmask_b32_e64 v15, v15, v227, s[24:25]
	v_cndmask_b32_e64 v14, v14, v227, s[22:23]
	v_cndmask_b32_e64 v13, v13, v227, s[20:21]
	v_cndmask_b32_e64 v12, v12, v227, s[18:19]
	v_cndmask_b32_e64 v11, v11, v227, s[16:17]
	v_cndmask_b32_e64 v10, v10, v227, s[14:15]
	v_cndmask_b32_e64 v9, v9, v227, s[12:13]
	v_cndmask_b32_e64 v8, v8, v227, s[10:11]
	v_cndmask_b32_e64 v7, v7, v227, s[8:9]
	v_cndmask_b32_e64 v6, v6, v227, s[6:7]
	v_cndmask_b32_e64 v5, v5, v227, s[0:1]
	v_cndmask_b32_e32 v4, v4, v227, vcc

; #define LAS __attribute__((address_space(3)))
; #define DMA_GROUP(t_) do { const int kt_ = ((t_) + 3 < NT) ? (t_) + 3 : NT - 1; int vt_ = ((t_) + 2 < NT) ? (t_) + 2 : NT - 1; vt_ = vt_ < 0 ? 0 : vt_; DMA_K(kt_, ((t_) + 3) & 3); DMA_V(vt_, ((t_) + 2) & 3); } while (0)
; template <bool FIXM> __device__ __forceinline__ void diff_unit(int b, int h, int qb, float lam, const bf16* U, const bf16* VTa, bf16* Y, const float* subg, const float* qgain, const int* pos, unsigned char* lds, int tid, int wid, int lane) {
;     ...
;         DMA_GROUP(-3); DMA_GROUP(-2); DMA_GROUP(-1);
;         asm volatile("s_waitcnt vmcnt(6)" ::: "memory");
;         __builtin_amdgcn_s_barrier();
;         float m = -INFINITY, l = 0.f;
; #pragma unroll
;         for (int db = 0; db < 4; ++db) o[db] = f32x16{};
;         u32x4 pwA[4], pwB[4];
; #pragma unroll
;         for (int i = 0; i < 4; ++i) { pwA[i] = u32x4{0u, 0u, 0u, 0u}; pwB[i] = pwA[i]; }
;         const LAS unsigned char* kfp = (const LAS unsigned char*)lds + prow * 128; const LAS unsigned char* vfp = (const LAS unsigned char*)lds + 4 * DK_BYTES + r32 * 128;
;         unsigned kofs[4], vofs[4];
; #pragma unroll
;         for (int k4 = 0; k4 < 4; ++k4) { kofs[k4] = ((2 * k4 + hi) ^ ((prow >> 1) & 7)) * 16; vofs[k4] = ((2 * k4 + hi) ^ ((r32 >> 1) & 7)) * 16; }
.LBB0_385:
	s_add_i32 s93, s76, -4
	s_add_i32 s92, s72, s76
	s_add_i32 s0, s76, -1
	s_cmp_lt_u32 s0, s82
	s_cselect_b32 s78, s0, s33
	s_add_i32 s91, s76, -2
	s_cmp_lt_u32 s91, s82
	s_cselect_b32 s84, s91, s33
	s_mul_i32 s98, s78, 0x58000
	s_add_u32 s98, s100, s98
	s_addc_u32 s99, s101, 0
	s_and_b32 s0, s77, 0x6000
	s_add_i32 m0, s67, s0
	s_lshl_b64 s[0:1], s[84:85], 7
	s_add_u32 s0, s74, s0
	s_addc_u32 s1, s75, s1
	global_load_lds_dwordx4 v202, s[98:99]
	s_add_i32 s98, s2, 0xc000
	s_and_b32 s98, s98, 0xc000
	s_add_i32 s98, s67, s98
	s_add_i32 m0, s98, 0x8000
	s_nop 0
	global_load_lds_dwordx4 v204, s[0:1]
	s_add_i32 m0, s98, 0xa000
	s_add_u32 s0, s0, 0x400000
	s_addc_u32 s1, s1, 0
	global_load_lds_dwordx4 v204, s[0:1]
	s_and_b32 s0, s2, 0xc000
	s_cmp_le_u32 s93, s83
	v_add_u32_e32 v243, s0, v230
	s_cselect_b64 s[96:97], -1, 0
	s_cmp_gt_u32 s93, s83
	s_mov_b64 s[0:1], -1
	s_cbranch_scc1 .LBB0_389
	s_cmp_eq_u32 s93, 1
	s_cbranch_scc1 .Lmy_oddqk_first
	s_add_i32 s0, s77, 0xffffa000
	s_and_b32 s0, s0, 0x6000
	v_add_u32_e32 v244, s0, v229
	v_add_u32_e32 v245, v244, v232
	ds_read_b128 v[2:5], v245
	ds_read_b128 v[10:13], v241
	ds_read_b128 v[6:9], v245 offset:4096
	v_add_u32_e32 v245, v244, v234
	ds_read_b128 v[18:21], v245
	ds_read_b128 v[14:17], v241 offset:1024
	ds_read_b128 v[22:25], v245 offset:4096
	v_add_u32_e32 v245, v244, v236
	ds_read_b128 v[26:29], v245
	ds_read_b128 v[34:37], v241 offset:2048
	ds_read_b128 v[30:33], v245 offset:4096
	v_add_u32_e32 v245, v244, v238
	ds_read_b128 v[38:41], v245
	ds_read_b128 v[46:49], v241 offset:3072
	ds_read_b128 v[42:45], v245 offset:4096
	s_waitcnt lgkmcnt(10)
	v_mfma_f32_32x32x16_bf16 v[146:161], v[2:5], v[10:13], 0
	v_exp_f32_e32 v246, v50
	v_exp_f32_e32 v247, v51
	v_add_f32_e32 v242, v246, v242
	v_add_f32_e32 v242, v247, v242
	v_cvt_pk_bf16_f32 v170, v246, v247
	s_waitcnt lgkmcnt(9)
	v_mfma_f32_32x32x16_bf16 v[130:145], v[6:9], v[10:13], 0
	v_exp_f32_e32 v246, v52
	v_exp_f32_e32 v247, v53
	v_add_f32_e32 v242, v246, v242
	v_add_f32_e32 v242, v247, v242
	v_cvt_pk_bf16_f32 v171, v246, v247
	s_waitcnt lgkmcnt(7)
	v_mfma_f32_32x32x16_bf16 v[146:161], v[18:21], v[14:17], v[146:161]
	v_exp_f32_e32 v246, v54
	v_exp_f32_e32 v247, v55
	v_add_f32_e32 v242, v246, v242
	v_add_f32_e32 v242, v247, v242
	v_cvt_pk_bf16_f32 v172, v246, v247
	s_waitcnt lgkmcnt(6)
	v_mfma_f32_32x32x16_bf16 v[130:145], v[22:25], v[14:17], v[130:145]
	v_exp_f32_e32 v246, v56
	v_exp_f32_e32 v247, v57
	v_add_f32_e32 v242, v246, v242
	v_add_f32_e32 v242, v247, v242
	v_cvt_pk_bf16_f32 v173, v246, v247
	s_waitcnt lgkmcnt(4)
	v_mfma_f32_32x32x16_bf16 v[146:161], v[26:29], v[34:37], v[146:161]
	v_exp_f32_e32 v246, v58
	v_exp_f32_e32 v247, v59
	v_add_f32_e32 v242, v246, v242
	v_add_f32_e32 v242, v247, v242
	v_cvt_pk_bf16_f32 v174, v246, v247
	s_waitcnt lgkmcnt(3)
	v_mfma_f32_32x32x16_bf16 v[130:145], v[30:33], v[34:37], v[130:145]
	v_exp_f32_e32 v246, v60
	v_exp_f32_e32 v247, v61
	v_add_f32_e32 v242, v246, v242
	v_add_f32_e32 v242, v247, v242
	v_cvt_pk_bf16_f32 v175, v246, v247
	s_waitcnt lgkmcnt(1)
	v_mfma_f32_32x32x16_bf16 v[146:161], v[38:41], v[46:49], v[146:161]
	v_exp_f32_e32 v246, v62
	v_exp_f32_e32 v247, v63
	v_add_f32_e32 v242, v246, v242
	v_add_f32_e32 v242, v247, v242
	v_cvt_pk_bf16_f32 v176, v246, v247
	s_waitcnt lgkmcnt(0)
	v_mfma_f32_32x32x16_bf16 v[130:145], v[42:45], v[46:49], v[130:145]
	v_exp_f32_e32 v246, v64
	v_exp_f32_e32 v247, v65
	v_add_f32_e32 v242, v246, v242
	v_add_f32_e32 v242, v247, v242
	v_cvt_pk_bf16_f32 v177, v246, v247
	s_branch .Lmy_oddqk_join

.LBB0_393:
	s_waitcnt vmcnt(6) lgkmcnt(0)
	s_cmp_ge_u32 s93, s82
	s_barrier
	s_cbranch_scc1 .LBB0_402
	s_cmp_lt_u32 s93, s73
	s_cselect_b32 s0, s76, s33
	s_mul_i32 s98, s0, 0x58000
	s_add_u32 s98, s100, s98
	s_addc_u32 s99, s101, 0
	s_add_i32 s0, s77, 0xffffa000
	s_mov_b32 s79, s85
	s_and_b32 s0, s0, 0x6000
	s_add_i32 m0, s67, s0
	s_lshl_b64 s[0:1], s[78:79], 7
	s_add_u32 s0, s74, s0
	s_addc_u32 s1, s75, s1
	global_load_lds_dwordx4 v202, s[98:99]
	s_add_i32 s98, s2, 0x10000
	s_and_b32 s98, s98, 0xc000
	s_add_i32 s98, s67, s98
	s_add_i32 m0, s98, 0x8000
	s_nop 0
	global_load_lds_dwordx4 v204, s[0:1]
	s_add_i32 m0, s98, 0xa000
	s_add_u32 s0, s0, 0x400000
	s_addc_u32 s1, s1, 0
	global_load_lds_dwordx4 v204, s[0:1]
	s_add_i32 s0, s2, 0x4000
	s_and_b32 s0, s0, 0xc000
	v_add_u32_e32 v248, s0, v230
	s_cmp_ge_u32 s93, s83
	s_mov_b64 s[0:1], -1
	s_cbranch_scc0 .LBB0_398
	s_andn2_b64 vcc, exec, s[96:97]
	s_cbranch_vccnz .LBB0_397
	v_exp_f32_e32 v246, v130
	v_exp_f32_e32 v247, v131
	v_add_f32_e32 v0, v246, v0
	v_add_f32_e32 v0, v247, v0
	v_cvt_pk_bf16_f32 v150, v246, v247
	v_exp_f32_e32 v246, v132
	v_exp_f32_e32 v247, v133
	v_add_f32_e32 v0, v246, v0
	v_add_f32_e32 v0, v247, v0
	v_cvt_pk_bf16_f32 v151, v246, v247
	v_exp_f32_e32 v246, v134
	v_exp_f32_e32 v247, v135
	v_add_f32_e32 v0, v246, v0
	v_add_f32_e32 v0, v247, v0
	v_cvt_pk_bf16_f32 v152, v246, v247
	v_exp_f32_e32 v246, v136
	v_exp_f32_e32 v247, v137
	v_add_f32_e32 v0, v246, v0
	v_add_f32_e32 v0, v247, v0
	v_cvt_pk_bf16_f32 v153, v246, v247
	v_exp_f32_e32 v246, v138
	v_exp_f32_e32 v247, v139
	v_add_f32_e32 v0, v246, v0
	v_add_f32_e32 v0, v247, v0
	v_cvt_pk_bf16_f32 v130, v246, v247
	v_exp_f32_e32 v246, v140
	v_exp_f32_e32 v247, v141
	v_add_f32_e32 v0, v246, v0
	v_add_f32_e32 v0, v247, v0
	v_cvt_pk_bf16_f32 v131, v246, v247
	v_exp_f32_e32 v246, v142
	v_exp_f32_e32 v247, v143
	v_add_f32_e32 v0, v246, v0
	v_add_f32_e32 v0, v247, v0
	v_cvt_pk_bf16_f32 v132, v246, v247
	v_exp_f32_e32 v246, v144
	v_exp_f32_e32 v247, v145
	v_add_f32_e32 v0, v246, v0
	v_add_f32_e32 v0, v247, v0
	v_cvt_pk_bf16_f32 v133, v246, v247
	v_add_u32_e32 v10, v248, v233
	ds_read_b128 v[2:5], v10 offset:32768
	ds_read_b128 v[6:9], v10 offset:36864
	s_waitcnt lgkmcnt(0)
	v_mfma_f32_32x32x16_bf16 v[114:129], v[2:5], v[178:181], v[114:129]
	ds_read_b128 v[2:5], v10 offset:40960
	ds_read_b128 v[136:139], v10 offset:45056
	v_mfma_f32_32x32x16_bf16 v[98:113], v[6:9], v[178:181], v[98:113]
	s_waitcnt lgkmcnt(0)
	v_mfma_f32_32x32x16_bf16 v[82:97], v[2:5], v[178:181], v[82:97]
	v_mfma_f32_32x32x16_bf16 v[66:81], v[136:139], v[178:181], v[66:81]
	v_add_u32_e32 v135, v248, v235
	ds_read_b128 v[136:139], v135 offset:32768
	s_waitcnt lgkmcnt(0)
	v_mfma_f32_32x32x16_bf16 v[114:129], v[136:139], v[146:149], v[114:129]
	ds_read_b128 v[136:139], v135 offset:36864
	s_waitcnt lgkmcnt(0)
	v_mfma_f32_32x32x16_bf16 v[98:113], v[136:139], v[146:149], v[98:113]
	ds_read_b128 v[136:139], v135 offset:40960
	s_waitcnt lgkmcnt(0)
	v_mfma_f32_32x32x16_bf16 v[82:97], v[136:139], v[146:149], v[82:97]
	ds_read_b128 v[136:139], v135 offset:45056
	s_waitcnt lgkmcnt(0)
	v_mfma_f32_32x32x16_bf16 v[66:81], v[136:139], v[146:149], v[66:81]
	v_add_u32_e32 v135, v248, v237
	ds_read_b128 v[136:139], v135 offset:32768
	s_waitcnt lgkmcnt(0)
	v_mfma_f32_32x32x16_bf16 v[114:129], v[136:139], v[150:153], v[114:129]
	ds_read_b128 v[136:139], v135 offset:36864
	s_waitcnt lgkmcnt(0)
	v_mfma_f32_32x32x16_bf16 v[98:113], v[136:139], v[150:153], v[98:113]
	ds_read_b128 v[136:139], v135 offset:40960
	s_waitcnt lgkmcnt(0)
	v_mfma_f32_32x32x16_bf16 v[82:97], v[136:139], v[150:153], v[82:97]
	ds_read_b128 v[136:139], v135 offset:45056
	s_waitcnt lgkmcnt(0)
	v_mfma_f32_32x32x16_bf16 v[66:81], v[136:139], v[150:153], v[66:81]
	v_add_u32_e32 v135, v248, v239
	ds_read_b128 v[136:139], v135 offset:32768
	s_waitcnt lgkmcnt(0)
	v_mfma_f32_32x32x16_bf16 v[114:129], v[136:139], v[130:133], v[114:129]
	ds_read_b128 v[136:139], v135 offset:36864
	s_waitcnt lgkmcnt(0)
	v_mfma_f32_32x32x16_bf16 v[98:113], v[136:139], v[130:133], v[98:113]
	ds_read_b128 v[136:139], v135 offset:40960
	s_waitcnt lgkmcnt(0)
	v_mfma_f32_32x32x16_bf16 v[82:97], v[136:139], v[130:133], v[82:97]
	ds_read_b128 v[136:139], v135 offset:45056
	s_waitcnt lgkmcnt(0)
	v_mfma_f32_32x32x16_bf16 v[66:81], v[136:139], v[130:133], v[66:81]

; __global__ void __launch_bounds__(NWAVES * 64, 2) hybrid_fwd(Args args) {
	.amdhsa_kernel _Z10hybrid_fwd4Args
		.amdhsa_group_segment_fixed_size 0
		.amdhsa_private_segment_fixed_size 0
		.amdhsa_kernarg_size 464
		.amdhsa_user_sgpr_count 2
		.amdhsa_user_sgpr_dispatch_ptr 0
		.amdhsa_user_sgpr_queue_ptr 0
		.amdhsa_user_sgpr_kernarg_segment_ptr 1
		.amdhsa_user_sgpr_dispatch_id 0
		.amdhsa_user_sgpr_kernarg_preload_length 0
		.amdhsa_user_sgpr_kernarg_preload_offset 0
		.amdhsa_user_sgpr_private_segment_size 0
		.amdhsa_uses_dynamic_stack 0
		.amdhsa_enable_private_segment 0
		.amdhsa_system_sgpr_workgroup_id_x 1
		.amdhsa_system_sgpr_workgroup_id_y 0
		.amdhsa_system_sgpr_workgroup_id_z 0
		.amdhsa_system_sgpr_workgroup_info 0
		.amdhsa_system_vgpr_workitem_id 2
		.amdhsa_next_free_vgpr 256
		.amdhsa_next_free_sgpr 102
		.amdhsa_accum_offset 256
		.amdhsa_reserve_vcc 1
		.amdhsa_float_round_mode_32 0
		.amdhsa_float_round_mode_16_64 0
		.amdhsa_float_denorm_mode_32 3
		.amdhsa_float_denorm_mode_16_64 3
		.amdhsa_dx10_clamp 1
		.amdhsa_ieee_mode 1
		.amdhsa_fp16_overflow 0
		.amdhsa_tg_split 0
		.amdhsa_exception_fp_ieee_invalid_op 0
		.amdhsa_exception_fp_denorm_src 0
		.amdhsa_exception_fp_ieee_div_zero 0
		.amdhsa_exception_fp_ieee_overflow 0
		.amdhsa_exception_fp_ieee_underflow 0
		.amdhsa_exception_fp_ieee_inexact 0
		.amdhsa_exception_int_div_zero 0
	.end_amdhsa_kernel

; __global__ void __launch_bounds__(NWAVES * 64, 2) hybrid_fwd(Args args) {
amdhsa.kernels:
  - .agpr_count:     0
    .args:
      - .offset:         0
        .size:           208
        .value_kind:     by_value
      - .offset:         208
        .size:           4
        .value_kind:     hidden_block_count_x
      - .offset:         212
        .size:           4
        .value_kind:     hidden_block_count_y
      - .offset:         216
        .size:           4
        .value_kind:     hidden_block_count_z
      - .offset:         220
        .size:           2
        .value_kind:     hidden_group_size_x
      - .offset:         222
        .size:           2
        .value_kind:     hidden_group_size_y
      - .offset:         224
        .size:           2
        .value_kind:     hidden_group_size_z
      - .offset:         226
        .size:           2
        .value_kind:     hidden_remainder_x
      - .offset:         228
        .size:           2
        .value_kind:     hidden_remainder_y
      - .offset:         230
        .size:           2
        .value_kind:     hidden_remainder_z
      - .offset:         248
        .size:           8
        .value_kind:     hidden_global_offset_x
      - .offset:         256
        .size:           8
        .value_kind:     hidden_global_offset_y
      - .offset:         264
        .size:           8
        .value_kind:     hidden_global_offset_z
      - .offset:         272
        .size:           2
        .value_kind:     hidden_grid_dims
      - .offset:         296
        .size:           8
        .value_kind:     hidden_multigrid_sync_arg
      - .offset:         328
        .size:           4
        .value_kind:     hidden_dynamic_lds_size
    .group_segment_fixed_size: 0
    .kernarg_segment_align: 8
    .kernarg_segment_size: 464
    .language:       OpenCL C
    .language_version:
      - 2
      - 0
    .max_flat_workgroup_size: 512
    .name:           _Z10hybrid_fwd4Args
    .private_segment_fixed_size: 0
    .sgpr_count:     108
    .sgpr_spill_count: 143
    .symbol:         _Z10hybrid_fwd4Args.kd
    .uniform_work_group_size: 1
    .uses_dynamic_stack: false
    .vgpr_count:     256
    .vgpr_spill_count: 0
    .wavefront_size: 64
